# EVIN epilogue rewritten by hand (row-stat loads pipelined 4 deep); dropped the vmcnt(0) inside the accumulator zeroing of six GEMM instances so prologue/prefetch DMA stays in flight into the main loop
# baseline (speedup 1.0000x reference)
.LBB0_1085:
	v_mov_b32_e32 v121, 0
	s_andn2_b64 vcc, exec, s[14:15]
	v_mov_b32_e32 v120, v121
	v_mov_b32_e32 v119, v121
	v_mov_b32_e32 v118, v121
	v_mov_b32_e32 v117, v121
	v_mov_b32_e32 v116, v121
	v_mov_b32_e32 v115, v121
	v_mov_b32_e32 v114, v121
	v_mov_b32_e32 v105, v121
	v_mov_b32_e32 v104, v121
	v_mov_b32_e32 v103, v121
	v_mov_b32_e32 v102, v121
	v_mov_b32_e32 v101, v121
	v_mov_b32_e32 v100, v121
	v_mov_b32_e32 v99, v121
	v_mov_b32_e32 v98, v121
	v_mov_b32_e32 v89, v121
	v_mov_b32_e32 v88, v121
	v_mov_b32_e32 v87, v121
	v_mov_b32_e32 v86, v121
	v_mov_b32_e32 v85, v121
	v_mov_b32_e32 v84, v121
	v_mov_b32_e32 v83, v121
	v_mov_b32_e32 v82, v121
	v_mov_b32_e32 v73, v121
	v_mov_b32_e32 v72, v121
	v_mov_b32_e32 v71, v121
	v_mov_b32_e32 v70, v121
	v_mov_b32_e32 v69, v121
	v_mov_b32_e32 v68, v121
	v_mov_b32_e32 v67, v121
	v_mov_b32_e32 v66, v121
	v_mov_b32_e32 v129, v121
	v_mov_b32_e32 v128, v121
	v_mov_b32_e32 v127, v121
	v_mov_b32_e32 v126, v121
	v_mov_b32_e32 v125, v121
	v_mov_b32_e32 v124, v121
	v_mov_b32_e32 v123, v121
	v_mov_b32_e32 v122, v121
	v_mov_b32_e32 v113, v121
	v_mov_b32_e32 v112, v121
	v_mov_b32_e32 v111, v121
	v_mov_b32_e32 v110, v121
	v_mov_b32_e32 v109, v121
	v_mov_b32_e32 v108, v121
	v_mov_b32_e32 v107, v121
	v_mov_b32_e32 v106, v121
	v_mov_b32_e32 v97, v121
	v_mov_b32_e32 v96, v121
	v_mov_b32_e32 v95, v121
	v_mov_b32_e32 v94, v121
	v_mov_b32_e32 v93, v121
	v_mov_b32_e32 v92, v121
	v_mov_b32_e32 v91, v121
	v_mov_b32_e32 v90, v121
	v_mov_b32_e32 v81, v121
	v_mov_b32_e32 v80, v121
	v_mov_b32_e32 v79, v121
	v_mov_b32_e32 v78, v121
	v_mov_b32_e32 v77, v121
	v_mov_b32_e32 v76, v121
	v_mov_b32_e32 v75, v121
	v_mov_b32_e32 v74, v121
	v_mov_b32_e32 v57, v121
	v_mov_b32_e32 v56, v121
	v_mov_b32_e32 v55, v121
	v_mov_b32_e32 v54, v121
	v_mov_b32_e32 v53, v121
	v_mov_b32_e32 v52, v121
	v_mov_b32_e32 v51, v121
	v_mov_b32_e32 v50, v121
	v_mov_b32_e32 v41, v121
	v_mov_b32_e32 v40, v121
	v_mov_b32_e32 v39, v121
	v_mov_b32_e32 v38, v121
	v_mov_b32_e32 v37, v121
	v_mov_b32_e32 v36, v121
	v_mov_b32_e32 v35, v121
	v_mov_b32_e32 v34, v121
	v_mov_b32_e32 v25, v121
	v_mov_b32_e32 v24, v121
	v_mov_b32_e32 v23, v121
	v_mov_b32_e32 v22, v121
	v_mov_b32_e32 v21, v121
	v_mov_b32_e32 v20, v121
	v_mov_b32_e32 v19, v121
	v_mov_b32_e32 v18, v121
	v_mov_b32_e32 v9, v121
	v_mov_b32_e32 v8, v121
	v_mov_b32_e32 v7, v121
	v_mov_b32_e32 v6, v121
	v_mov_b32_e32 v5, v121
	v_mov_b32_e32 v4, v121
	v_mov_b32_e32 v3, v121
	v_mov_b32_e32 v2, v121
	v_mov_b32_e32 v65, v121
	v_mov_b32_e32 v64, v121
	v_mov_b32_e32 v63, v121
	v_mov_b32_e32 v62, v121
	v_mov_b32_e32 v61, v121
	v_mov_b32_e32 v60, v121
	v_mov_b32_e32 v59, v121
	v_mov_b32_e32 v58, v121
	v_mov_b32_e32 v49, v121
	v_mov_b32_e32 v48, v121
	v_mov_b32_e32 v47, v121
	v_mov_b32_e32 v46, v121
	v_mov_b32_e32 v45, v121
	v_mov_b32_e32 v44, v121
	v_mov_b32_e32 v43, v121
	v_mov_b32_e32 v42, v121
	v_mov_b32_e32 v33, v121
	v_mov_b32_e32 v32, v121
	v_mov_b32_e32 v31, v121
	v_mov_b32_e32 v30, v121
	v_mov_b32_e32 v29, v121
	v_mov_b32_e32 v28, v121
	v_mov_b32_e32 v27, v121
	v_mov_b32_e32 v26, v121
	v_mov_b32_e32 v17, v121
	v_mov_b32_e32 v16, v121
	v_mov_b32_e32 v15, v121
	v_mov_b32_e32 v14, v121
	v_mov_b32_e32 v13, v121
	v_mov_b32_e32 v12, v121
	v_mov_b32_e32 v11, v121
	v_mov_b32_e32 v10, v121
	s_cbranch_vccnz .LBB0_1089
	s_add_u32 s20, s20, 0x80
	s_addc_u32 s21, s21, 0
	s_add_u32 s44, s22, 0x100
	s_addc_u32 s46, s23, 0
	s_mov_b32 s22, 0

.LBB0_1177:
	v_mov_b32_e32 v129, 0
	s_andn2_b64 vcc, exec, s[18:19]
	v_mov_b32_e32 v128, v129
	v_mov_b32_e32 v127, v129
	v_mov_b32_e32 v126, v129
	v_mov_b32_e32 v125, v129
	v_mov_b32_e32 v124, v129
	v_mov_b32_e32 v123, v129
	v_mov_b32_e32 v122, v129
	v_mov_b32_e32 v113, v129
	v_mov_b32_e32 v112, v129
	v_mov_b32_e32 v111, v129
	v_mov_b32_e32 v110, v129
	v_mov_b32_e32 v109, v129
	v_mov_b32_e32 v108, v129
	v_mov_b32_e32 v107, v129
	v_mov_b32_e32 v106, v129
	v_mov_b32_e32 v97, v129
	v_mov_b32_e32 v96, v129
	v_mov_b32_e32 v95, v129
	v_mov_b32_e32 v94, v129
	v_mov_b32_e32 v93, v129
	v_mov_b32_e32 v92, v129
	v_mov_b32_e32 v91, v129
	v_mov_b32_e32 v90, v129
	v_mov_b32_e32 v81, v129
	v_mov_b32_e32 v80, v129
	v_mov_b32_e32 v79, v129
	v_mov_b32_e32 v78, v129
	v_mov_b32_e32 v77, v129
	v_mov_b32_e32 v76, v129
	v_mov_b32_e32 v75, v129
	v_mov_b32_e32 v74, v129
	v_mov_b32_e32 v121, v129
	v_mov_b32_e32 v120, v129
	v_mov_b32_e32 v119, v129
	v_mov_b32_e32 v118, v129
	v_mov_b32_e32 v117, v129
	v_mov_b32_e32 v116, v129
	v_mov_b32_e32 v115, v129
	v_mov_b32_e32 v114, v129
	v_mov_b32_e32 v105, v129
	v_mov_b32_e32 v104, v129
	v_mov_b32_e32 v103, v129
	v_mov_b32_e32 v102, v129
	v_mov_b32_e32 v101, v129
	v_mov_b32_e32 v100, v129
	v_mov_b32_e32 v99, v129
	v_mov_b32_e32 v98, v129
	v_mov_b32_e32 v89, v129
	v_mov_b32_e32 v88, v129
	v_mov_b32_e32 v87, v129
	v_mov_b32_e32 v86, v129
	v_mov_b32_e32 v85, v129
	v_mov_b32_e32 v84, v129
	v_mov_b32_e32 v83, v129
	v_mov_b32_e32 v82, v129
	v_mov_b32_e32 v73, v129
	v_mov_b32_e32 v72, v129
	v_mov_b32_e32 v71, v129
	v_mov_b32_e32 v70, v129
	v_mov_b32_e32 v69, v129
	v_mov_b32_e32 v68, v129
	v_mov_b32_e32 v67, v129
	v_mov_b32_e32 v66, v129
	v_mov_b32_e32 v65, v129
	v_mov_b32_e32 v64, v129
	v_mov_b32_e32 v63, v129
	v_mov_b32_e32 v62, v129
	v_mov_b32_e32 v61, v129
	v_mov_b32_e32 v60, v129
	v_mov_b32_e32 v59, v129
	v_mov_b32_e32 v58, v129
	v_mov_b32_e32 v49, v129
	v_mov_b32_e32 v48, v129
	v_mov_b32_e32 v47, v129
	v_mov_b32_e32 v46, v129
	v_mov_b32_e32 v45, v129
	v_mov_b32_e32 v44, v129
	v_mov_b32_e32 v43, v129
	v_mov_b32_e32 v42, v129
	v_mov_b32_e32 v33, v129
	v_mov_b32_e32 v32, v129
	v_mov_b32_e32 v31, v129
	v_mov_b32_e32 v30, v129
	v_mov_b32_e32 v29, v129
	v_mov_b32_e32 v28, v129
	v_mov_b32_e32 v27, v129
	v_mov_b32_e32 v26, v129
	v_mov_b32_e32 v17, v129
	v_mov_b32_e32 v16, v129
	v_mov_b32_e32 v15, v129
	v_mov_b32_e32 v14, v129
	v_mov_b32_e32 v13, v129
	v_mov_b32_e32 v12, v129
	v_mov_b32_e32 v11, v129
	v_mov_b32_e32 v10, v129
	v_mov_b32_e32 v57, v129
	v_mov_b32_e32 v56, v129
	v_mov_b32_e32 v55, v129
	v_mov_b32_e32 v54, v129
	v_mov_b32_e32 v53, v129
	v_mov_b32_e32 v52, v129
	v_mov_b32_e32 v51, v129
	v_mov_b32_e32 v50, v129
	v_mov_b32_e32 v41, v129
	v_mov_b32_e32 v40, v129
	v_mov_b32_e32 v39, v129
	v_mov_b32_e32 v38, v129
	v_mov_b32_e32 v37, v129
	v_mov_b32_e32 v36, v129
	v_mov_b32_e32 v35, v129
	v_mov_b32_e32 v34, v129
	v_mov_b32_e32 v25, v129
	v_mov_b32_e32 v24, v129
	v_mov_b32_e32 v23, v129
	v_mov_b32_e32 v22, v129
	v_mov_b32_e32 v21, v129
	v_mov_b32_e32 v20, v129
	v_mov_b32_e32 v19, v129
	v_mov_b32_e32 v18, v129
	v_mov_b32_e32 v9, v129
	v_mov_b32_e32 v8, v129
	v_mov_b32_e32 v7, v129
	v_mov_b32_e32 v6, v129
	v_mov_b32_e32 v5, v129
	v_mov_b32_e32 v4, v129
	v_mov_b32_e32 v3, v129
	v_mov_b32_e32 v2, v129
	s_cbranch_vccnz .LBB0_1181
	s_add_u32 s61, s28, 0x100
	s_waitcnt lgkmcnt(0)
	s_addc_u32 s62, s29, 0
	s_mov_b32 s34, 0
	s_mov_b64 s[28:29], 0

.LBB0_1233:
	v_mov_b32_e32 v125, 0
	s_andn2_b64 vcc, exec, s[16:17]
	v_mov_b32_e32 v124, v125
	v_mov_b32_e32 v123, v125
	v_mov_b32_e32 v122, v125
	v_mov_b32_e32 v129, v125
	v_mov_b32_e32 v128, v125
	v_mov_b32_e32 v127, v125
	v_mov_b32_e32 v126, v125
	v_mov_b32_e32 v113, v125
	v_mov_b32_e32 v112, v125
	v_mov_b32_e32 v111, v125
	v_mov_b32_e32 v110, v125
	v_mov_b32_e32 v109, v125
	v_mov_b32_e32 v108, v125
	v_mov_b32_e32 v107, v125
	v_mov_b32_e32 v106, v125
	v_mov_b32_e32 v97, v125
	v_mov_b32_e32 v96, v125
	v_mov_b32_e32 v95, v125
	v_mov_b32_e32 v94, v125
	v_mov_b32_e32 v93, v125
	v_mov_b32_e32 v92, v125
	v_mov_b32_e32 v91, v125
	v_mov_b32_e32 v90, v125
	v_mov_b32_e32 v81, v125
	v_mov_b32_e32 v80, v125
	v_mov_b32_e32 v79, v125
	v_mov_b32_e32 v78, v125
	v_mov_b32_e32 v77, v125
	v_mov_b32_e32 v76, v125
	v_mov_b32_e32 v75, v125
	v_mov_b32_e32 v74, v125
	v_mov_b32_e32 v121, v125
	v_mov_b32_e32 v120, v125
	v_mov_b32_e32 v119, v125
	v_mov_b32_e32 v118, v125
	v_mov_b32_e32 v117, v125
	v_mov_b32_e32 v116, v125
	v_mov_b32_e32 v115, v125
	v_mov_b32_e32 v114, v125
	v_mov_b32_e32 v105, v125
	v_mov_b32_e32 v104, v125
	v_mov_b32_e32 v103, v125
	v_mov_b32_e32 v102, v125
	v_mov_b32_e32 v101, v125
	v_mov_b32_e32 v100, v125
	v_mov_b32_e32 v99, v125
	v_mov_b32_e32 v98, v125
	v_mov_b32_e32 v89, v125
	v_mov_b32_e32 v88, v125
	v_mov_b32_e32 v87, v125
	v_mov_b32_e32 v86, v125
	v_mov_b32_e32 v85, v125
	v_mov_b32_e32 v84, v125
	v_mov_b32_e32 v83, v125
	v_mov_b32_e32 v82, v125
	v_mov_b32_e32 v73, v125
	v_mov_b32_e32 v72, v125
	v_mov_b32_e32 v71, v125
	v_mov_b32_e32 v70, v125
	v_mov_b32_e32 v69, v125
	v_mov_b32_e32 v68, v125
	v_mov_b32_e32 v67, v125
	v_mov_b32_e32 v66, v125
	v_mov_b32_e32 v65, v125
	v_mov_b32_e32 v64, v125
	v_mov_b32_e32 v63, v125
	v_mov_b32_e32 v62, v125
	v_mov_b32_e32 v61, v125
	v_mov_b32_e32 v60, v125
	v_mov_b32_e32 v59, v125
	v_mov_b32_e32 v58, v125
	v_mov_b32_e32 v49, v125
	v_mov_b32_e32 v48, v125
	v_mov_b32_e32 v47, v125
	v_mov_b32_e32 v46, v125
	v_mov_b32_e32 v45, v125
	v_mov_b32_e32 v44, v125
	v_mov_b32_e32 v43, v125
	v_mov_b32_e32 v42, v125
	v_mov_b32_e32 v33, v125
	v_mov_b32_e32 v32, v125
	v_mov_b32_e32 v31, v125
	v_mov_b32_e32 v30, v125
	v_mov_b32_e32 v29, v125
	v_mov_b32_e32 v28, v125
	v_mov_b32_e32 v27, v125
	v_mov_b32_e32 v26, v125
	v_mov_b32_e32 v17, v125
	v_mov_b32_e32 v16, v125
	v_mov_b32_e32 v15, v125
	v_mov_b32_e32 v14, v125
	v_mov_b32_e32 v13, v125
	v_mov_b32_e32 v12, v125
	v_mov_b32_e32 v11, v125
	v_mov_b32_e32 v10, v125
	v_mov_b32_e32 v57, v125
	v_mov_b32_e32 v56, v125
	v_mov_b32_e32 v55, v125
	v_mov_b32_e32 v54, v125
	v_mov_b32_e32 v53, v125
	v_mov_b32_e32 v52, v125
	v_mov_b32_e32 v51, v125
	v_mov_b32_e32 v50, v125
	v_mov_b32_e32 v41, v125
	v_mov_b32_e32 v40, v125
	v_mov_b32_e32 v39, v125
	v_mov_b32_e32 v38, v125
	v_mov_b32_e32 v37, v125
	v_mov_b32_e32 v36, v125
	v_mov_b32_e32 v35, v125
	v_mov_b32_e32 v34, v125
	v_mov_b32_e32 v25, v125
	v_mov_b32_e32 v24, v125
	v_mov_b32_e32 v23, v125
	v_mov_b32_e32 v22, v125
	v_mov_b32_e32 v21, v125
	v_mov_b32_e32 v20, v125
	v_mov_b32_e32 v19, v125
	v_mov_b32_e32 v18, v125
	v_mov_b32_e32 v9, v125
	v_mov_b32_e32 v8, v125
	v_mov_b32_e32 v7, v125
	v_mov_b32_e32 v6, v125
	v_mov_b32_e32 v5, v125
	v_mov_b32_e32 v4, v125
	v_mov_b32_e32 v3, v125
	v_mov_b32_e32 v2, v125
	s_cbranch_vccnz .LBB0_1237
	s_add_u32 s0, s0, 0x80
	s_addc_u32 s1, s1, 0
	s_add_u32 s24, s24, 0x100
	s_addc_u32 s25, s25, 0
	s_mov_b32 s4, 0

.LBB0_1577:
	v_mov_b32_e32 v125, 0
	s_andn2_b64 vcc, exec, s[12:13]
	v_mov_b32_e32 v124, v125
	v_mov_b32_e32 v123, v125
	v_mov_b32_e32 v122, v125
	v_mov_b32_e32 v129, v125
	v_mov_b32_e32 v128, v125
	v_mov_b32_e32 v127, v125
	v_mov_b32_e32 v126, v125
	v_mov_b32_e32 v113, v125
	v_mov_b32_e32 v112, v125
	v_mov_b32_e32 v111, v125
	v_mov_b32_e32 v110, v125
	v_mov_b32_e32 v109, v125
	v_mov_b32_e32 v108, v125
	v_mov_b32_e32 v107, v125
	v_mov_b32_e32 v106, v125
	v_mov_b32_e32 v97, v125
	v_mov_b32_e32 v96, v125
	v_mov_b32_e32 v95, v125
	v_mov_b32_e32 v94, v125
	v_mov_b32_e32 v93, v125
	v_mov_b32_e32 v92, v125
	v_mov_b32_e32 v91, v125
	v_mov_b32_e32 v90, v125
	v_mov_b32_e32 v81, v125
	v_mov_b32_e32 v80, v125
	v_mov_b32_e32 v79, v125
	v_mov_b32_e32 v78, v125
	v_mov_b32_e32 v77, v125
	v_mov_b32_e32 v76, v125
	v_mov_b32_e32 v75, v125
	v_mov_b32_e32 v74, v125
	v_mov_b32_e32 v121, v125
	v_mov_b32_e32 v120, v125
	v_mov_b32_e32 v119, v125
	v_mov_b32_e32 v118, v125
	v_mov_b32_e32 v117, v125
	v_mov_b32_e32 v116, v125
	v_mov_b32_e32 v115, v125
	v_mov_b32_e32 v114, v125
	v_mov_b32_e32 v105, v125
	v_mov_b32_e32 v104, v125
	v_mov_b32_e32 v103, v125
	v_mov_b32_e32 v102, v125
	v_mov_b32_e32 v101, v125
	v_mov_b32_e32 v100, v125
	v_mov_b32_e32 v99, v125
	v_mov_b32_e32 v98, v125
	v_mov_b32_e32 v89, v125
	v_mov_b32_e32 v88, v125
	v_mov_b32_e32 v87, v125
	v_mov_b32_e32 v86, v125
	v_mov_b32_e32 v85, v125
	v_mov_b32_e32 v84, v125
	v_mov_b32_e32 v83, v125
	v_mov_b32_e32 v82, v125
	v_mov_b32_e32 v73, v125
	v_mov_b32_e32 v72, v125
	v_mov_b32_e32 v71, v125
	v_mov_b32_e32 v70, v125
	v_mov_b32_e32 v69, v125
	v_mov_b32_e32 v68, v125
	v_mov_b32_e32 v67, v125
	v_mov_b32_e32 v66, v125
	v_mov_b32_e32 v65, v125
	v_mov_b32_e32 v64, v125
	v_mov_b32_e32 v63, v125
	v_mov_b32_e32 v62, v125
	v_mov_b32_e32 v61, v125
	v_mov_b32_e32 v60, v125
	v_mov_b32_e32 v59, v125
	v_mov_b32_e32 v58, v125
	v_mov_b32_e32 v49, v125
	v_mov_b32_e32 v48, v125
	v_mov_b32_e32 v47, v125
	v_mov_b32_e32 v46, v125
	v_mov_b32_e32 v45, v125
	v_mov_b32_e32 v44, v125
	v_mov_b32_e32 v43, v125
	v_mov_b32_e32 v42, v125
	v_mov_b32_e32 v33, v125
	v_mov_b32_e32 v32, v125
	v_mov_b32_e32 v31, v125
	v_mov_b32_e32 v30, v125
	v_mov_b32_e32 v29, v125
	v_mov_b32_e32 v28, v125
	v_mov_b32_e32 v27, v125
	v_mov_b32_e32 v26, v125
	v_mov_b32_e32 v17, v125
	v_mov_b32_e32 v16, v125
	v_mov_b32_e32 v15, v125
	v_mov_b32_e32 v14, v125
	v_mov_b32_e32 v13, v125
	v_mov_b32_e32 v12, v125
	v_mov_b32_e32 v11, v125
	v_mov_b32_e32 v10, v125
	v_mov_b32_e32 v57, v125
	v_mov_b32_e32 v56, v125
	v_mov_b32_e32 v55, v125
	v_mov_b32_e32 v54, v125
	v_mov_b32_e32 v53, v125
	v_mov_b32_e32 v52, v125
	v_mov_b32_e32 v51, v125
	v_mov_b32_e32 v50, v125
	v_mov_b32_e32 v41, v125
	v_mov_b32_e32 v40, v125
	v_mov_b32_e32 v39, v125
	v_mov_b32_e32 v38, v125
	v_mov_b32_e32 v37, v125
	v_mov_b32_e32 v36, v125
	v_mov_b32_e32 v35, v125
	v_mov_b32_e32 v34, v125
	v_mov_b32_e32 v25, v125
	v_mov_b32_e32 v24, v125
	v_mov_b32_e32 v23, v125
	v_mov_b32_e32 v22, v125
	v_mov_b32_e32 v21, v125
	v_mov_b32_e32 v20, v125
	v_mov_b32_e32 v19, v125
	v_mov_b32_e32 v18, v125
	v_mov_b32_e32 v9, v125
	v_mov_b32_e32 v8, v125
	v_mov_b32_e32 v7, v125
	v_mov_b32_e32 v6, v125
	v_mov_b32_e32 v5, v125
	v_mov_b32_e32 v4, v125
	v_mov_b32_e32 v3, v125
	v_mov_b32_e32 v2, v125
	s_cbranch_vccnz .LBB0_1580
	s_add_u32 s0, s0, 0x80
	s_addc_u32 s1, s1, 0
	s_add_u32 s37, s18, 0x100
	s_addc_u32 s38, s19, 0
	s_mov_b32 s18, 0

.LBB0_1580:
	v_lshl_add_u32 v180, s33, 8, v156
	v_mov_b32_e32 v181, 0
	v_add_u32_e32 v178, 0x80, v180
	v_mov_b32_e32 v179, 0
	v_lshlrev_b64 v[244:245], 6, v[180:181]
	v_lshlrev_b64 v[246:247], 6, v[178:179]
	v_lshl_add_u64 v[244:245], s[72:73], 0, v[244:245]
	v_lshl_add_u64 v[246:247], s[72:73], 0, v[246:247]
	global_load_dwordx4 v[196:199], v[244:245], off offset:48
	global_load_dwordx4 v[200:203], v[244:245], off offset:32
	global_load_dwordx4 v[204:207], v[244:245], off offset:16
	global_load_dwordx4 v[208:211], v[244:245], off
	global_load_dwordx4 v[212:215], v[244:245], off offset:1072
	global_load_dwordx4 v[216:219], v[244:245], off offset:1056
	global_load_dwordx4 v[220:223], v[244:245], off offset:1040
	global_load_dwordx4 v[224:227], v[244:245], off offset:1024
	global_load_dwordx4 v[228:231], v[244:245], off offset:2096
	global_load_dwordx4 v[232:235], v[244:245], off offset:2080
	global_load_dwordx4 v[236:239], v[244:245], off offset:2064
	global_load_dwordx4 v[240:243], v[244:245], off offset:2048
	global_load_dwordx4 v[160:163], v[244:245], off offset:3120
	global_load_dwordx4 v[164:167], v[244:245], off offset:3104
	global_load_dwordx4 v[168:171], v[244:245], off offset:3088
	global_load_dwordx4 v[174:177], v[244:245], off offset:3072
	s_and_b64 vcc, exec, s[14:15]
	s_cbranch_vccz .LBB0_1582
	s_barrier
.LBB0_1582:
	v_readlane_b32 s18, v254, 19
	s_lshl_b32 s0, s36, 8
	v_readlane_b32 s19, v254, 20
	s_ashr_i32 s1, s0, 31
	s_lshl_b64 s[0:1], s[0:1], 1
	s_nop 1
	v_mov_b64_e32 v[248:249], s[18:19]
	v_lshl_add_u64 v[248:249], v[248:249], 0, s[0:1]
	v_lshl_add_u64 v[248:249], v[248:249], 0, s[54:55]
	v_lshl_add_u64 v[248:249], v[248:249], 0, v[0:1]
	s_waitcnt vmcnt(12)
	v_add_f32_e32 v154, v208, v209
	v_add_f32_e32 v155, v210, v211
	v_add_f32_e32 v154, v154, v155
	v_add_f32_e32 v155, v204, v205
	v_add_f32_e32 v159, v206, v207
	v_add_f32_e32 v155, v155, v159
	v_add_f32_e32 v154, v154, v155
	v_add_f32_e32 v155, v200, v201
	v_add_f32_e32 v159, v202, v203
	v_add_f32_e32 v155, v155, v159
	v_add_f32_e32 v154, v154, v155
	v_add_f32_e32 v155, v196, v197
	v_add_f32_e32 v159, v198, v199
	v_add_f32_e32 v155, v155, v159
	v_add_f32_e32 v154, v154, v155
	v_fmamk_f32 v154, v154, 0x3a800000, v184
	v_rsq_f32_e32 v182, v154
	global_load_dwordx4 v[196:199], v[246:247], off offset:48
	global_load_dwordx4 v[200:203], v[246:247], off offset:32
	global_load_dwordx4 v[204:207], v[246:247], off offset:16
	global_load_dwordx4 v[208:211], v[246:247], off
	v_mad_i64_i32 v[178:179], vcc, v180, s84, v[248:249]
	v_pk_mul_f32 v[122:123], v[122:123], v[182:183] op_sel_hi:[1,0]
	v_pk_mul_f32 v[124:125], v[124:125], v[182:183] op_sel_hi:[1,0]
	v_pk_mul_f32 v[126:127], v[126:127], v[182:183] op_sel_hi:[1,0]
	v_pk_mul_f32 v[128:129], v[128:129], v[182:183] op_sel_hi:[1,0]
	v_cvt_pk_bf16_f32 v122, v122, v123
	v_cvt_pk_bf16_f32 v123, v124, v125
	v_cvt_pk_bf16_f32 v124, v126, v127
	v_cvt_pk_bf16_f32 v125, v128, v129
	global_store_dwordx4 v[178:179], v[122:125], off nt
	v_pk_mul_f32 v[118:119], v[118:119], v[182:183] op_sel_hi:[1,0]
	v_pk_mul_f32 v[120:121], v[120:121], v[182:183] op_sel_hi:[1,0]
	v_pk_mul_f32 v[114:115], v[114:115], v[182:183] op_sel_hi:[1,0]
	v_pk_mul_f32 v[116:117], v[116:117], v[182:183] op_sel_hi:[1,0]
	v_cvt_pk_bf16_f32 v118, v118, v119
	v_cvt_pk_bf16_f32 v119, v120, v121
	v_cvt_pk_bf16_f32 v120, v114, v115
	v_cvt_pk_bf16_f32 v121, v116, v117
	global_store_dwordx4 v[178:179], v[118:121], off offset:256 nt
	s_waitcnt vmcnt(14)
	v_add_f32_e32 v154, v224, v225
	v_add_f32_e32 v155, v226, v227
	v_add_f32_e32 v154, v154, v155
	v_add_f32_e32 v155, v220, v221
	v_add_f32_e32 v159, v222, v223
	v_add_f32_e32 v155, v155, v159
	v_add_f32_e32 v154, v154, v155
	v_add_f32_e32 v155, v216, v217
	v_add_f32_e32 v159, v218, v219
	v_add_f32_e32 v155, v155, v159
	v_add_f32_e32 v154, v154, v155
	v_add_f32_e32 v155, v212, v213
	v_add_f32_e32 v159, v214, v215
	v_add_f32_e32 v155, v155, v159
	v_add_f32_e32 v154, v154, v155
	v_fmamk_f32 v154, v154, 0x3a800000, v184
	v_rsq_f32_e32 v182, v154
	global_load_dwordx4 v[212:215], v[246:247], off offset:1072
	global_load_dwordx4 v[216:219], v[246:247], off offset:1056
	global_load_dwordx4 v[220:223], v[246:247], off offset:1040
	global_load_dwordx4 v[224:227], v[246:247], off offset:1024
	v_add_u32_e32 v178, 16, v180
	v_mad_i64_i32 v[178:179], vcc, v178, s84, v[248:249]
	v_pk_mul_f32 v[110:111], v[110:111], v[182:183] op_sel_hi:[1,0]
	v_pk_mul_f32 v[112:113], v[112:113], v[182:183] op_sel_hi:[1,0]
	v_pk_mul_f32 v[106:107], v[106:107], v[182:183] op_sel_hi:[1,0]
	v_pk_mul_f32 v[108:109], v[108:109], v[182:183] op_sel_hi:[1,0]
	v_cvt_pk_bf16_f32 v110, v110, v111
	v_cvt_pk_bf16_f32 v111, v112, v113
	v_cvt_pk_bf16_f32 v112, v106, v107
	v_cvt_pk_bf16_f32 v113, v108, v109
	global_store_dwordx4 v[178:179], v[110:113], off nt
	v_pk_mul_f32 v[102:103], v[102:103], v[182:183] op_sel_hi:[1,0]
	v_pk_mul_f32 v[104:105], v[104:105], v[182:183] op_sel_hi:[1,0]
	v_pk_mul_f32 v[98:99], v[98:99], v[182:183] op_sel_hi:[1,0]
	v_pk_mul_f32 v[100:101], v[100:101], v[182:183] op_sel_hi:[1,0]
	v_cvt_pk_bf16_f32 v102, v102, v103
	v_cvt_pk_bf16_f32 v103, v104, v105
	v_cvt_pk_bf16_f32 v104, v98, v99
	v_cvt_pk_bf16_f32 v105, v100, v101
	global_store_dwordx4 v[178:179], v[102:105], off offset:256 nt
	s_waitcnt vmcnt(16)
	v_add_f32_e32 v154, v240, v241
	v_add_f32_e32 v155, v242, v243
	v_add_f32_e32 v154, v154, v155
	v_add_f32_e32 v155, v236, v237
	v_add_f32_e32 v159, v238, v239
	v_add_f32_e32 v155, v155, v159
	v_add_f32_e32 v154, v154, v155
	v_add_f32_e32 v155, v232, v233
	v_add_f32_e32 v159, v234, v235
	v_add_f32_e32 v155, v155, v159
	v_add_f32_e32 v154, v154, v155
	v_add_f32_e32 v155, v228, v229
	v_add_f32_e32 v159, v230, v231
	v_add_f32_e32 v155, v155, v159
	v_add_f32_e32 v154, v154, v155
	v_fmamk_f32 v154, v154, 0x3a800000, v184
	v_rsq_f32_e32 v182, v154
	global_load_dwordx4 v[228:231], v[246:247], off offset:2096
	global_load_dwordx4 v[232:235], v[246:247], off offset:2080
	global_load_dwordx4 v[236:239], v[246:247], off offset:2064
	global_load_dwordx4 v[240:243], v[246:247], off offset:2048
	v_add_u32_e32 v178, 32, v180
	v_mad_i64_i32 v[178:179], vcc, v178, s84, v[248:249]
	v_pk_mul_f32 v[94:95], v[94:95], v[182:183] op_sel_hi:[1,0]
	v_pk_mul_f32 v[96:97], v[96:97], v[182:183] op_sel_hi:[1,0]
	v_pk_mul_f32 v[90:91], v[90:91], v[182:183] op_sel_hi:[1,0]
	v_pk_mul_f32 v[92:93], v[92:93], v[182:183] op_sel_hi:[1,0]
	v_cvt_pk_bf16_f32 v94, v94, v95
	v_cvt_pk_bf16_f32 v95, v96, v97
	v_cvt_pk_bf16_f32 v96, v90, v91
	v_cvt_pk_bf16_f32 v97, v92, v93
	global_store_dwordx4 v[178:179], v[94:97], off nt
	v_pk_mul_f32 v[86:87], v[86:87], v[182:183] op_sel_hi:[1,0]
	v_pk_mul_f32 v[88:89], v[88:89], v[182:183] op_sel_hi:[1,0]
	v_pk_mul_f32 v[82:83], v[82:83], v[182:183] op_sel_hi:[1,0]
	v_pk_mul_f32 v[84:85], v[84:85], v[182:183] op_sel_hi:[1,0]
	v_cvt_pk_bf16_f32 v86, v86, v87
	v_cvt_pk_bf16_f32 v87, v88, v89
	v_cvt_pk_bf16_f32 v88, v82, v83
	v_cvt_pk_bf16_f32 v89, v84, v85
	global_store_dwordx4 v[178:179], v[86:89], off offset:256 nt
	s_waitcnt vmcnt(18)
	v_add_f32_e32 v154, v174, v175
	v_add_f32_e32 v155, v176, v177
	v_add_f32_e32 v154, v154, v155
	v_add_f32_e32 v155, v168, v169
	v_add_f32_e32 v159, v170, v171
	v_add_f32_e32 v155, v155, v159
	v_add_f32_e32 v154, v154, v155
	v_add_f32_e32 v155, v164, v165
	v_add_f32_e32 v159, v166, v167
	v_add_f32_e32 v155, v155, v159
	v_add_f32_e32 v154, v154, v155
	v_add_f32_e32 v155, v160, v161
	v_add_f32_e32 v159, v162, v163
	v_add_f32_e32 v155, v155, v159
	v_add_f32_e32 v154, v154, v155
	v_fmamk_f32 v154, v154, 0x3a800000, v184
	v_rsq_f32_e32 v182, v154
	global_load_dwordx4 v[160:163], v[246:247], off offset:3120
	global_load_dwordx4 v[164:167], v[246:247], off offset:3104
	global_load_dwordx4 v[168:171], v[246:247], off offset:3088
	global_load_dwordx4 v[174:177], v[246:247], off offset:3072
	v_add_u32_e32 v178, 48, v180
	v_mad_i64_i32 v[178:179], vcc, v178, s84, v[248:249]
	v_pk_mul_f32 v[78:79], v[78:79], v[182:183] op_sel_hi:[1,0]
	v_pk_mul_f32 v[80:81], v[80:81], v[182:183] op_sel_hi:[1,0]
	v_pk_mul_f32 v[74:75], v[74:75], v[182:183] op_sel_hi:[1,0]
	v_pk_mul_f32 v[76:77], v[76:77], v[182:183] op_sel_hi:[1,0]
	v_cvt_pk_bf16_f32 v78, v78, v79
	v_cvt_pk_bf16_f32 v79, v80, v81
	v_cvt_pk_bf16_f32 v80, v74, v75
	v_cvt_pk_bf16_f32 v81, v76, v77
	global_store_dwordx4 v[178:179], v[78:81], off nt
	v_pk_mul_f32 v[70:71], v[70:71], v[182:183] op_sel_hi:[1,0]
	v_pk_mul_f32 v[72:73], v[72:73], v[182:183] op_sel_hi:[1,0]
	v_pk_mul_f32 v[66:67], v[66:67], v[182:183] op_sel_hi:[1,0]
	v_pk_mul_f32 v[68:69], v[68:69], v[182:183] op_sel_hi:[1,0]
	v_cvt_pk_bf16_f32 v70, v70, v71
	v_cvt_pk_bf16_f32 v71, v72, v73
	v_cvt_pk_bf16_f32 v72, v66, v67
	v_cvt_pk_bf16_f32 v73, v68, v69
	global_store_dwordx4 v[178:179], v[70:73], off offset:256 nt
	s_waitcnt vmcnt(20)
	v_add_f32_e32 v154, v208, v209
	v_add_f32_e32 v155, v210, v211
	v_add_f32_e32 v154, v154, v155
	v_add_f32_e32 v155, v204, v205
	v_add_f32_e32 v159, v206, v207
	v_add_f32_e32 v155, v155, v159
	v_add_f32_e32 v154, v154, v155
	v_add_f32_e32 v155, v200, v201
	v_add_f32_e32 v159, v202, v203
	v_add_f32_e32 v155, v155, v159
	v_add_f32_e32 v154, v154, v155
	v_add_f32_e32 v155, v196, v197
	v_add_f32_e32 v159, v198, v199
	v_add_f32_e32 v155, v155, v159
	v_add_f32_e32 v154, v154, v155
	v_fmamk_f32 v154, v154, 0x3a800000, v184
	v_rsq_f32_e32 v182, v154
	v_add_u32_e32 v178, 128, v180
	v_mad_i64_i32 v[178:179], vcc, v178, s84, v[248:249]
	v_pk_mul_f32 v[62:63], v[62:63], v[182:183] op_sel_hi:[1,0]
	v_pk_mul_f32 v[64:65], v[64:65], v[182:183] op_sel_hi:[1,0]
	v_pk_mul_f32 v[58:59], v[58:59], v[182:183] op_sel_hi:[1,0]
	v_pk_mul_f32 v[60:61], v[60:61], v[182:183] op_sel_hi:[1,0]
	v_cvt_pk_bf16_f32 v62, v62, v63
	v_cvt_pk_bf16_f32 v63, v64, v65
	v_cvt_pk_bf16_f32 v64, v58, v59
	v_cvt_pk_bf16_f32 v65, v60, v61
	global_store_dwordx4 v[178:179], v[62:65], off nt
	v_pk_mul_f32 v[54:55], v[54:55], v[182:183] op_sel_hi:[1,0]
	v_pk_mul_f32 v[56:57], v[56:57], v[182:183] op_sel_hi:[1,0]
	v_pk_mul_f32 v[50:51], v[50:51], v[182:183] op_sel_hi:[1,0]
	v_pk_mul_f32 v[52:53], v[52:53], v[182:183] op_sel_hi:[1,0]
	v_cvt_pk_bf16_f32 v54, v54, v55
	v_cvt_pk_bf16_f32 v55, v56, v57
	v_cvt_pk_bf16_f32 v56, v50, v51
	v_cvt_pk_bf16_f32 v57, v52, v53
	global_store_dwordx4 v[178:179], v[54:57], off offset:256 nt
	s_waitcnt vmcnt(16)
	v_add_f32_e32 v154, v224, v225
	v_add_f32_e32 v155, v226, v227
	v_add_f32_e32 v154, v154, v155
	v_add_f32_e32 v155, v220, v221
	v_add_f32_e32 v159, v222, v223
	v_add_f32_e32 v155, v155, v159
	v_add_f32_e32 v154, v154, v155
	v_add_f32_e32 v155, v216, v217
	v_add_f32_e32 v159, v218, v219
	v_add_f32_e32 v155, v155, v159
	v_add_f32_e32 v154, v154, v155
	v_add_f32_e32 v155, v212, v213
	v_add_f32_e32 v159, v214, v215
	v_add_f32_e32 v155, v155, v159
	v_add_f32_e32 v154, v154, v155
	v_fmamk_f32 v154, v154, 0x3a800000, v184
	v_rsq_f32_e32 v182, v154
	v_add_u32_e32 v178, 144, v180
	v_mad_i64_i32 v[178:179], vcc, v178, s84, v[248:249]
	v_pk_mul_f32 v[46:47], v[46:47], v[182:183] op_sel_hi:[1,0]
	v_pk_mul_f32 v[48:49], v[48:49], v[182:183] op_sel_hi:[1,0]
	v_pk_mul_f32 v[42:43], v[42:43], v[182:183] op_sel_hi:[1,0]
	v_pk_mul_f32 v[44:45], v[44:45], v[182:183] op_sel_hi:[1,0]
	v_cvt_pk_bf16_f32 v46, v46, v47
	v_cvt_pk_bf16_f32 v47, v48, v49
	v_cvt_pk_bf16_f32 v48, v42, v43
	v_cvt_pk_bf16_f32 v49, v44, v45
	global_store_dwordx4 v[178:179], v[46:49], off nt
	v_pk_mul_f32 v[38:39], v[38:39], v[182:183] op_sel_hi:[1,0]
	v_pk_mul_f32 v[40:41], v[40:41], v[182:183] op_sel_hi:[1,0]
	v_pk_mul_f32 v[34:35], v[34:35], v[182:183] op_sel_hi:[1,0]
	v_pk_mul_f32 v[36:37], v[36:37], v[182:183] op_sel_hi:[1,0]
	v_cvt_pk_bf16_f32 v38, v38, v39
	v_cvt_pk_bf16_f32 v39, v40, v41
	v_cvt_pk_bf16_f32 v40, v34, v35
	v_cvt_pk_bf16_f32 v41, v36, v37
	global_store_dwordx4 v[178:179], v[38:41], off offset:256 nt
	s_waitcnt vmcnt(12)
	v_add_f32_e32 v154, v240, v241
	v_add_f32_e32 v155, v242, v243
	v_add_f32_e32 v154, v154, v155
	v_add_f32_e32 v155, v236, v237
	v_add_f32_e32 v159, v238, v239
	v_add_f32_e32 v155, v155, v159
	v_add_f32_e32 v154, v154, v155
	v_add_f32_e32 v155, v232, v233
	v_add_f32_e32 v159, v234, v235
	v_add_f32_e32 v155, v155, v159
	v_add_f32_e32 v154, v154, v155
	v_add_f32_e32 v155, v228, v229
	v_add_f32_e32 v159, v230, v231
	v_add_f32_e32 v155, v155, v159
	v_add_f32_e32 v154, v154, v155
	v_fmamk_f32 v154, v154, 0x3a800000, v184
	v_rsq_f32_e32 v182, v154
	v_add_u32_e32 v178, 160, v180
	v_mad_i64_i32 v[178:179], vcc, v178, s84, v[248:249]
	v_pk_mul_f32 v[30:31], v[30:31], v[182:183] op_sel_hi:[1,0]
	v_pk_mul_f32 v[32:33], v[32:33], v[182:183] op_sel_hi:[1,0]
	v_pk_mul_f32 v[26:27], v[26:27], v[182:183] op_sel_hi:[1,0]
	v_pk_mul_f32 v[28:29], v[28:29], v[182:183] op_sel_hi:[1,0]
	v_cvt_pk_bf16_f32 v30, v30, v31
	v_cvt_pk_bf16_f32 v31, v32, v33
	v_cvt_pk_bf16_f32 v32, v26, v27
	v_cvt_pk_bf16_f32 v33, v28, v29
	global_store_dwordx4 v[178:179], v[30:33], off nt
	v_pk_mul_f32 v[22:23], v[22:23], v[182:183] op_sel_hi:[1,0]
	v_pk_mul_f32 v[24:25], v[24:25], v[182:183] op_sel_hi:[1,0]
	v_pk_mul_f32 v[18:19], v[18:19], v[182:183] op_sel_hi:[1,0]
	v_pk_mul_f32 v[20:21], v[20:21], v[182:183] op_sel_hi:[1,0]
	v_cvt_pk_bf16_f32 v22, v22, v23
	v_cvt_pk_bf16_f32 v23, v24, v25
	v_cvt_pk_bf16_f32 v24, v18, v19
	v_cvt_pk_bf16_f32 v25, v20, v21
	global_store_dwordx4 v[178:179], v[22:25], off offset:256 nt
	s_waitcnt vmcnt(8)
	v_add_f32_e32 v154, v174, v175
	v_add_f32_e32 v155, v176, v177
	v_add_f32_e32 v154, v154, v155
	v_add_f32_e32 v155, v168, v169
	v_add_f32_e32 v159, v170, v171
	v_add_f32_e32 v155, v155, v159
	v_add_f32_e32 v154, v154, v155
	v_add_f32_e32 v155, v164, v165
	v_add_f32_e32 v159, v166, v167
	v_add_f32_e32 v155, v155, v159
	v_add_f32_e32 v154, v154, v155
	v_add_f32_e32 v155, v160, v161
	v_add_f32_e32 v159, v162, v163
	v_add_f32_e32 v155, v155, v159
	v_add_f32_e32 v154, v154, v155
	v_fmamk_f32 v154, v154, 0x3a800000, v184
	v_rsq_f32_e32 v182, v154
	v_add_u32_e32 v178, 176, v180
	v_mad_i64_i32 v[178:179], vcc, v178, s84, v[248:249]
	v_pk_mul_f32 v[14:15], v[14:15], v[182:183] op_sel_hi:[1,0]
	v_pk_mul_f32 v[16:17], v[16:17], v[182:183] op_sel_hi:[1,0]
	v_pk_mul_f32 v[10:11], v[10:11], v[182:183] op_sel_hi:[1,0]
	v_pk_mul_f32 v[12:13], v[12:13], v[182:183] op_sel_hi:[1,0]
	v_cvt_pk_bf16_f32 v14, v14, v15
	v_cvt_pk_bf16_f32 v15, v16, v17
	v_cvt_pk_bf16_f32 v16, v10, v11
	v_cvt_pk_bf16_f32 v17, v12, v13
	global_store_dwordx4 v[178:179], v[14:17], off nt
	v_pk_mul_f32 v[6:7], v[6:7], v[182:183] op_sel_hi:[1,0]
	v_pk_mul_f32 v[8:9], v[8:9], v[182:183] op_sel_hi:[1,0]
	v_pk_mul_f32 v[2:3], v[2:3], v[182:183] op_sel_hi:[1,0]
	v_pk_mul_f32 v[4:5], v[4:5], v[182:183] op_sel_hi:[1,0]
	v_cvt_pk_bf16_f32 v6, v6, v7
	v_cvt_pk_bf16_f32 v7, v8, v9
	v_cvt_pk_bf16_f32 v8, v2, v3
	v_cvt_pk_bf16_f32 v9, v4, v5
	global_store_dwordx4 v[178:179], v[6:9], off offset:256 nt
	s_mov_b64 s[0:1], -1
	s_and_b64 vcc, exec, s[2:3]
	s_cbranch_vccnz .LBB0_1570
	s_andn2_b64 vcc, exec, s[10:11]
	s_cbranch_vccnz .LBB0_1569
	s_barrier
	s_branch .LBB0_1569

.LBB0_1608:
	v_mov_b32_e32 v125, 0
	s_andn2_b64 vcc, exec, s[14:15]
	v_mov_b32_e32 v124, v125
	v_mov_b32_e32 v123, v125
	v_mov_b32_e32 v122, v125
	v_mov_b32_e32 v129, v125
	v_mov_b32_e32 v128, v125
	v_mov_b32_e32 v127, v125
	v_mov_b32_e32 v126, v125
	v_mov_b32_e32 v113, v125
	v_mov_b32_e32 v112, v125
	v_mov_b32_e32 v111, v125
	v_mov_b32_e32 v110, v125
	v_mov_b32_e32 v109, v125
	v_mov_b32_e32 v108, v125
	v_mov_b32_e32 v107, v125
	v_mov_b32_e32 v106, v125
	v_mov_b32_e32 v97, v125
	v_mov_b32_e32 v96, v125
	v_mov_b32_e32 v95, v125
	v_mov_b32_e32 v94, v125
	v_mov_b32_e32 v93, v125
	v_mov_b32_e32 v92, v125
	v_mov_b32_e32 v91, v125
	v_mov_b32_e32 v90, v125
	v_mov_b32_e32 v81, v125
	v_mov_b32_e32 v80, v125
	v_mov_b32_e32 v79, v125
	v_mov_b32_e32 v78, v125
	v_mov_b32_e32 v77, v125
	v_mov_b32_e32 v76, v125
	v_mov_b32_e32 v75, v125
	v_mov_b32_e32 v74, v125
	v_mov_b32_e32 v121, v125
	v_mov_b32_e32 v120, v125
	v_mov_b32_e32 v119, v125
	v_mov_b32_e32 v118, v125
	v_mov_b32_e32 v117, v125
	v_mov_b32_e32 v116, v125
	v_mov_b32_e32 v115, v125
	v_mov_b32_e32 v114, v125
	v_mov_b32_e32 v105, v125
	v_mov_b32_e32 v104, v125
	v_mov_b32_e32 v103, v125
	v_mov_b32_e32 v102, v125
	v_mov_b32_e32 v101, v125
	v_mov_b32_e32 v100, v125
	v_mov_b32_e32 v99, v125
	v_mov_b32_e32 v98, v125
	v_mov_b32_e32 v89, v125
	v_mov_b32_e32 v88, v125
	v_mov_b32_e32 v87, v125
	v_mov_b32_e32 v86, v125
	v_mov_b32_e32 v85, v125
	v_mov_b32_e32 v84, v125
	v_mov_b32_e32 v83, v125
	v_mov_b32_e32 v82, v125
	v_mov_b32_e32 v73, v125
	v_mov_b32_e32 v72, v125
	v_mov_b32_e32 v71, v125
	v_mov_b32_e32 v70, v125
	v_mov_b32_e32 v69, v125
	v_mov_b32_e32 v68, v125
	v_mov_b32_e32 v67, v125
	v_mov_b32_e32 v66, v125
	v_mov_b32_e32 v65, v125
	v_mov_b32_e32 v64, v125
	v_mov_b32_e32 v63, v125
	v_mov_b32_e32 v62, v125
	v_mov_b32_e32 v61, v125
	v_mov_b32_e32 v60, v125
	v_mov_b32_e32 v59, v125
	v_mov_b32_e32 v58, v125
	v_mov_b32_e32 v49, v125
	v_mov_b32_e32 v48, v125
	v_mov_b32_e32 v47, v125
	v_mov_b32_e32 v46, v125
	v_mov_b32_e32 v45, v125
	v_mov_b32_e32 v44, v125
	v_mov_b32_e32 v43, v125
	v_mov_b32_e32 v42, v125
	v_mov_b32_e32 v33, v125
	v_mov_b32_e32 v32, v125
	v_mov_b32_e32 v31, v125
	v_mov_b32_e32 v30, v125
	v_mov_b32_e32 v29, v125
	v_mov_b32_e32 v28, v125
	v_mov_b32_e32 v27, v125
	v_mov_b32_e32 v26, v125
	v_mov_b32_e32 v17, v125
	v_mov_b32_e32 v16, v125
	v_mov_b32_e32 v15, v125
	v_mov_b32_e32 v14, v125
	v_mov_b32_e32 v13, v125
	v_mov_b32_e32 v12, v125
	v_mov_b32_e32 v11, v125
	v_mov_b32_e32 v10, v125
	v_mov_b32_e32 v57, v125
	v_mov_b32_e32 v56, v125
	v_mov_b32_e32 v55, v125
	v_mov_b32_e32 v54, v125
	v_mov_b32_e32 v53, v125
	v_mov_b32_e32 v52, v125
	v_mov_b32_e32 v51, v125
	v_mov_b32_e32 v50, v125
	v_mov_b32_e32 v41, v125
	v_mov_b32_e32 v40, v125
	v_mov_b32_e32 v39, v125
	v_mov_b32_e32 v38, v125
	v_mov_b32_e32 v37, v125
	v_mov_b32_e32 v36, v125
	v_mov_b32_e32 v35, v125
	v_mov_b32_e32 v34, v125
	v_mov_b32_e32 v25, v125
	v_mov_b32_e32 v24, v125
	v_mov_b32_e32 v23, v125
	v_mov_b32_e32 v22, v125
	v_mov_b32_e32 v21, v125
	v_mov_b32_e32 v20, v125
	v_mov_b32_e32 v19, v125
	v_mov_b32_e32 v18, v125
	v_mov_b32_e32 v9, v125
	v_mov_b32_e32 v8, v125
	v_mov_b32_e32 v7, v125
	v_mov_b32_e32 v6, v125
	v_mov_b32_e32 v5, v125
	v_mov_b32_e32 v4, v125
	s_waitcnt lgkmcnt(0)
	v_mov_b32_e32 v3, v125
	v_mov_b32_e32 v2, v125
	s_cbranch_vccnz .LBB0_1612
	s_add_u32 s0, s0, 0x80
	s_addc_u32 s1, s1, 0
	s_add_u32 s44, s20, 0x100
	s_addc_u32 s46, s21, 0
	s_mov_b32 s20, 0

.LBB0_1648:
	v_mov_b32_e32 v125, 0
	s_andn2_b64 vcc, exec, s[12:13]
	v_mov_b32_e32 v124, v125
	v_mov_b32_e32 v123, v125
	v_mov_b32_e32 v122, v125
	v_mov_b32_e32 v117, v125
	v_mov_b32_e32 v116, v125
	v_mov_b32_e32 v115, v125
	v_mov_b32_e32 v114, v125
	v_mov_b32_e32 v109, v125
	v_mov_b32_e32 v108, v125
	v_mov_b32_e32 v107, v125
	v_mov_b32_e32 v106, v125
	v_mov_b32_e32 v101, v125
	v_mov_b32_e32 v100, v125
	v_mov_b32_e32 v99, v125
	v_mov_b32_e32 v98, v125
	v_mov_b32_e32 v93, v125
	v_mov_b32_e32 v92, v125
	v_mov_b32_e32 v91, v125
	v_mov_b32_e32 v90, v125
	v_mov_b32_e32 v85, v125
	v_mov_b32_e32 v84, v125
	v_mov_b32_e32 v83, v125
	v_mov_b32_e32 v82, v125
	v_mov_b32_e32 v77, v125
	v_mov_b32_e32 v76, v125
	v_mov_b32_e32 v75, v125
	v_mov_b32_e32 v74, v125
	v_mov_b32_e32 v69, v125
	v_mov_b32_e32 v68, v125
	v_mov_b32_e32 v67, v125
	v_mov_b32_e32 v66, v125
	v_mov_b32_e32 v129, v125
	v_mov_b32_e32 v128, v125
	v_mov_b32_e32 v127, v125
	v_mov_b32_e32 v126, v125
	v_mov_b32_e32 v121, v125
	v_mov_b32_e32 v120, v125
	v_mov_b32_e32 v119, v125
	v_mov_b32_e32 v118, v125
	v_mov_b32_e32 v113, v125
	v_mov_b32_e32 v112, v125
	v_mov_b32_e32 v111, v125
	v_mov_b32_e32 v110, v125
	v_mov_b32_e32 v105, v125
	v_mov_b32_e32 v104, v125
	v_mov_b32_e32 v103, v125
	v_mov_b32_e32 v102, v125
	v_mov_b32_e32 v97, v125
	v_mov_b32_e32 v96, v125
	v_mov_b32_e32 v95, v125
	v_mov_b32_e32 v94, v125
	v_mov_b32_e32 v89, v125
	v_mov_b32_e32 v88, v125
	v_mov_b32_e32 v87, v125
	v_mov_b32_e32 v86, v125
	v_mov_b32_e32 v81, v125
	v_mov_b32_e32 v80, v125
	v_mov_b32_e32 v79, v125
	v_mov_b32_e32 v78, v125
	v_mov_b32_e32 v73, v125
	v_mov_b32_e32 v72, v125
	v_mov_b32_e32 v71, v125
	v_mov_b32_e32 v70, v125
	v_mov_b32_e32 v61, v125
	v_mov_b32_e32 v60, v125
	v_mov_b32_e32 v59, v125
	v_mov_b32_e32 v58, v125
	v_mov_b32_e32 v53, v125
	v_mov_b32_e32 v52, v125
	v_mov_b32_e32 v51, v125
	v_mov_b32_e32 v50, v125
	v_mov_b32_e32 v45, v125
	v_mov_b32_e32 v44, v125
	v_mov_b32_e32 v43, v125
	v_mov_b32_e32 v42, v125
	v_mov_b32_e32 v37, v125
	v_mov_b32_e32 v36, v125
	v_mov_b32_e32 v35, v125
	v_mov_b32_e32 v34, v125
	v_mov_b32_e32 v29, v125
	v_mov_b32_e32 v28, v125
	v_mov_b32_e32 v27, v125
	v_mov_b32_e32 v26, v125
	v_mov_b32_e32 v21, v125
	v_mov_b32_e32 v20, v125
	v_mov_b32_e32 v19, v125
	v_mov_b32_e32 v18, v125
	v_mov_b32_e32 v13, v125
	v_mov_b32_e32 v12, v125
	v_mov_b32_e32 v11, v125
	v_mov_b32_e32 v10, v125
	v_mov_b32_e32 v9, v125
	v_mov_b32_e32 v8, v125
	v_mov_b32_e32 v7, v125
	v_mov_b32_e32 v6, v125
	v_mov_b32_e32 v65, v125
	v_mov_b32_e32 v64, v125
	v_mov_b32_e32 v63, v125
	v_mov_b32_e32 v62, v125
	v_mov_b32_e32 v57, v125
	v_mov_b32_e32 v56, v125
	v_mov_b32_e32 v55, v125
	v_mov_b32_e32 v54, v125
	v_mov_b32_e32 v49, v125
	v_mov_b32_e32 v48, v125
	v_mov_b32_e32 v47, v125
	v_mov_b32_e32 v46, v125
	v_mov_b32_e32 v41, v125
	v_mov_b32_e32 v40, v125
	v_mov_b32_e32 v39, v125
	v_mov_b32_e32 v38, v125
	v_mov_b32_e32 v33, v125
	v_mov_b32_e32 v32, v125
	v_mov_b32_e32 v31, v125
	v_mov_b32_e32 v30, v125
	v_mov_b32_e32 v25, v125
	v_mov_b32_e32 v24, v125
	v_mov_b32_e32 v23, v125
	v_mov_b32_e32 v22, v125
	v_mov_b32_e32 v17, v125
	v_mov_b32_e32 v16, v125
	v_mov_b32_e32 v15, v125
	v_mov_b32_e32 v14, v125
	v_mov_b32_e32 v5, v125
	v_mov_b32_e32 v4, v125
	v_mov_b32_e32 v3, v125
	v_mov_b32_e32 v2, v125
	s_cbranch_vccnz .LBB0_1651
	s_add_u32 s0, s0, 0x80
	s_addc_u32 s1, s1, 0
	s_add_u32 s35, s18, 0x100
	s_addc_u32 s36, s19, 0
	s_mov_b32 s18, 0
